# fast path v2: LDS-DMA issue moved into first MFMA shadows, branch at loop top
# baseline (speedup 1.0000x reference)
; #define MFMA(a, b, c) __builtin_amdgcn_mfma_f32_32x32x16_bf16((a), (b), (c), 0, 0, 0)
; DI float fexp2(float x) { return __builtin_amdgcn_exp2f(x); }
; DI void diff_pass(const bf16_t* __restrict__ qrow  , const bf16_t* __restrict__ kg, const bf16_t* __restrict__ vg,
;                   int nkt, int q0, float negM2, f32x16 (&O)[4], float& lsum, char* lds) {
;     ...
;     for (int kt = 0; kt < nkt; ++kt) {
;         char* st = lds + (kt & 1) * 24576;
;         if (kt + 1 < nkt) {
;             char* st2 = lds + ((kt + 1) & 1) * 24576 + wb;
;             __builtin_amdgcn_global_load_lds((const unsigned*)(kgs + (size_t)(kt + 1) * 64 * 512), (lds_ptr_t)(st2), 16, 0, 0);
;             __builtin_amdgcn_global_load_lds((const unsigned*)(vgs + (kt + 1) * 64), (lds_ptr_t)(st2 + 8192), 16, 0, 0);
;             __builtin_amdgcn_global_load_lds((const unsigned*)(vgs + (size_t)64 * kS + (kt + 1) * 64), (lds_ptr_t)(st2 + 16384), 16, 0, 0);
;         }
;         __builtin_amdgcn_sched_barrier(0);
;         if (kt * 64 <= q0 + 31) {
;             f32x16 Sx[2];
;             {
;                 bf16x8 kf[2][4];
; #pragma unroll
;                 for (int kb = 0; kb < 2; ++kb)
; #pragma unroll
;                     for (int ks = 0; ks < 4; ++ks) kf[kb][ks] = *(const bf16x8*)(st + (32 * kb + l31) * 128 + (((2 * ks + h) ^ f) << 4));
;                 __builtin_amdgcn_sched_barrier(0);
; #pragma unroll
;                 for (int ks = 0; ks < 4; ++ks)
; #pragma unroll
;                     for (int kb = 0; kb < 2; ++kb) Sx[kb] = ks == 0 ? MFMA(kf[kb][0], qf[0], minit) : MFMA(kf[kb][ks], qf[ks], Sx[kb]);
;             }
;             if (kt * 64 + 63 > q0) {
; #pragma unroll
;                 for (int kb = 0; kb < 2; ++kb)
; #pragma unroll
;                     for (int i = 0; i < 16; ++i) {
;                         float p = fexp2(Sx[kb][i]);
;                         const int key = kt * 64 + 32 * kb + (i & 3) + 8 * (i >> 2) + 4 * h;
;                         if (key > qpos) p = 0.f;
;                         lsum += p; Sx[kb][i] = p;
;                     }
;             } else {
;                 float l0 = 0.f, l1 = 0.f;
; #pragma unroll
;                 for (int i = 0; i < 16; ++i) { const float p0 = fexp2(Sx[0][i]), p1 = fexp2(Sx[1][i]); l0 += p0; l1 += p1; Sx[0][i] = p0; Sx[1][i] = p1; }
;                 lsum += l0 + l1;
;             }
.Ldf_join:
	s_waitcnt vmcnt(0)
	s_add_i32 s55, s55, 64
	s_add_i32 s54, s54, 1
	s_mov_b64 s[28:29], 0x10000
	v_lshl_add_u64 v[164:165], v[164:165], 0, s[18:19]
	s_cmp_eq_u32 s35, s55
	v_lshl_add_u64 v[160:161], v[160:161], 0, s[28:29]
	s_waitcnt vmcnt(0) lgkmcnt(0)
	s_barrier
	s_cbranch_scc1 .LBB0_93
.LBB0_88:
	s_add_i32 s28, s55, 63
	v_cmp_le_i32_e32 vcc, s28, v148
	s_cbranch_vccnz .Ldf_fast
	s_and_b32 s30, 1, s54
	s_cselect_b32 s28, 0x6000, 0
	v_add_u32_e32 v0, s28, v187
	v_lshl_add_u64 v[2:3], v[160:161], 0, v[158:159]
	v_readfirstlane_b32 s28, v0
	s_mov_b32 m0, s28
	s_mov_b64 s[28:29], 0x1b800080
	global_load_lds_dwordx4 v[2:3], off
	v_lshl_add_u64 v[2:3], v[164:165], 0, v[158:159]
	v_add_u32_e32 v6, 0x2000, v0
	v_lshl_add_u64 v[4:5], v[2:3], 0, s[28:29]
	v_readfirstlane_b32 s28, v6
	s_mov_b32 m0, s28
	s_mov_b64 s[28:29], 0x1b900080
	v_add_u32_e32 v0, 0x4000, v0
	v_lshl_add_u64 v[2:3], v[2:3], 0, s[28:29]
	v_readfirstlane_b32 s28, v0
	global_load_lds_dwordx4 v[4:5], off
	s_mov_b32 m0, s28
	s_nop 0
	global_load_lds_dwordx4 v[2:3], off
	v_cmp_le_i32_e32 vcc, s55, v171
	s_and_saveexec_b64 s[28:29], vcc
	s_cbranch_execz .LBB0_87
	s_cmp_eq_u32 s30, 1
	s_cselect_b32 s30, 0, 0x6000
	v_or_b32_e32 v0, s30, v188
	v_add_u32_e32 v195, v0, v189
	v_add_u32_e32 v194, v0, v190
	v_add_u32_e32 v193, v0, v191
	v_add_u32_e32 v0, v0, v192
	ds_read_b128 v[2:5], v195
	ds_read_b128 v[6:9], v195 offset:4096
	ds_read_b128 v[10:13], v194
	ds_read_b128 v[196:199], v194 offset:4096
	ds_read_b128 v[200:203], v193
	ds_read_b128 v[204:207], v193 offset:4096
	ds_read_b128 v[208:211], v0
	ds_read_b128 v[212:215], v0 offset:4096
	s_waitcnt lgkmcnt(0)
	v_mfma_f32_32x32x16_bf16 v[96:111], v[2:5], v[140:143], v[16:31]
	s_add_i32 s30, s55, 63
	v_cmp_le_i32_e32 vcc, s30, v148
	v_mfma_f32_32x32x16_bf16 v[112:127], v[6:9], v[140:143], v[16:31]
	v_mfma_f32_32x32x16_bf16 v[96:111], v[10:13], v[136:139], v[96:111]
	v_mfma_f32_32x32x16_bf16 v[112:127], v[196:199], v[136:139], v[112:127]
	v_mfma_f32_32x32x16_bf16 v[96:111], v[200:203], v[132:135], v[96:111]
	v_mfma_f32_32x32x16_bf16 v[112:127], v[204:207], v[132:135], v[112:127]
	v_mfma_f32_32x32x16_bf16 v[96:111], v[208:211], v[128:131], v[96:111]
	v_mfma_f32_32x32x16_bf16 v[112:127], v[212:215], v[128:131], v[112:127]
	s_nop 10
	v_exp_f32_e32 v2, v96
	v_exp_f32_e32 v4, v97
	v_exp_f32_e32 v6, v98
	v_exp_f32_e32 v8, v99
	v_exp_f32_e32 v10, v100
	v_exp_f32_e32 v12, v101
	v_exp_f32_e32 v14, v102
	v_exp_f32_e32 v3, v112
	v_exp_f32_e32 v5, v113
	v_exp_f32_e32 v7, v114
	v_exp_f32_e32 v9, v115
	v_exp_f32_e32 v11, v116
	v_exp_f32_e32 v13, v117
	v_exp_f32_e32 v15, v118
	v_exp_f32_e32 v96, v103
	v_exp_f32_e32 v97, v119
	v_exp_f32_e32 v100, v104
	v_exp_f32_e32 v101, v120
	v_exp_f32_e32 v104, v105
	v_exp_f32_e32 v105, v121
	v_exp_f32_e32 v98, v106
	v_exp_f32_e32 v99, v122
	v_exp_f32_e32 v102, v107
	v_exp_f32_e32 v103, v123
	v_exp_f32_e32 v106, v108
	v_exp_f32_e32 v107, v124
	v_exp_f32_e32 v108, v109
	v_exp_f32_e32 v109, v125
	v_exp_f32_e32 v112, v110
	v_exp_f32_e32 v113, v126
	v_exp_f32_e32 v110, v111
	v_exp_f32_e32 v111, v127
	s_and_saveexec_b64 s[30:31], vcc
	s_xor_b64 s[30:31], exec, s[30:31]
	s_cbranch_execz .LBB0_91
	v_pk_add_f32 v[114:115], v[2:3], 0 op_sel_hi:[1,0]
	s_nop 0
	v_pk_add_f32 v[114:115], v[4:5], v[114:115]
	s_nop 0
	v_pk_add_f32 v[114:115], v[6:7], v[114:115]
	s_nop 0
	v_pk_add_f32 v[114:115], v[8:9], v[114:115]
	s_nop 0
	v_pk_add_f32 v[114:115], v[10:11], v[114:115]
	s_nop 0
	v_pk_add_f32 v[114:115], v[12:13], v[114:115]
	s_nop 0
	v_pk_add_f32 v[114:115], v[14:15], v[114:115]
	s_nop 0
	v_pk_add_f32 v[114:115], v[96:97], v[114:115]
	s_nop 0
	v_pk_add_f32 v[114:115], v[100:101], v[114:115]
	s_nop 0
	v_pk_add_f32 v[114:115], v[104:105], v[114:115]
	s_nop 0
	v_pk_add_f32 v[114:115], v[98:99], v[114:115]
	s_nop 0
	v_pk_add_f32 v[114:115], v[102:103], v[114:115]
	s_nop 0
	v_pk_add_f32 v[114:115], v[106:107], v[114:115]
	s_nop 0
	v_pk_add_f32 v[114:115], v[108:109], v[114:115]
	s_nop 0
	v_pk_add_f32 v[114:115], v[112:113], v[114:115]
	s_nop 0
	v_pk_add_f32 v[114:115], v[110:111], v[114:115]
	s_nop 0
	v_add_f32_e32 v114, v114, v115
	v_add_f32_e32 v186, v186, v114

; DI void diff_pass(const bf16_t* __restrict__ qrow  , const bf16_t* __restrict__ kg, const bf16_t* __restrict__ vg,
;                   int nkt, int q0, float negM2, f32x16 (&O)[4], float& lsum, char* lds) {
;     ...
;         char* st = lds + (kt & 1) * 24576;
;         if (kt + 1 < nkt) {
;             char* st2 = lds + ((kt + 1) & 1) * 24576 + wb;
;             __builtin_amdgcn_global_load_lds((const unsigned*)(kgs + (size_t)(kt + 1) * 64 * 512), (lds_ptr_t)(st2), 16, 0, 0);
;             __builtin_amdgcn_global_load_lds((const unsigned*)(vgs + (kt + 1) * 64), (lds_ptr_t)(st2 + 8192), 16, 0, 0);
;             __builtin_amdgcn_global_load_lds((const unsigned*)(vgs + (size_t)64 * kS + (kt + 1) * 64), (lds_ptr_t)(st2 + 16384), 16, 0, 0);
;         }
;         __builtin_amdgcn_sched_barrier(0);
;         if (kt * 64 <= q0 + 31) {
;             f32x16 Sx[2];
;             {
;                 bf16x8 kf[2][4];
; #pragma unroll
;                 for (int kb = 0; kb < 2; ++kb)
; #pragma unroll
;                     for (int ks = 0; ks < 4; ++ks) kf[kb][ks] = *(const bf16x8*)(st + (32 * kb + l31) * 128 + (((2 * ks + h) ^ f) << 4));
;                 __builtin_amdgcn_sched_barrier(0);
; #pragma unroll
;                 for (int ks = 0; ks < 4; ++ks)
; #pragma unroll
;                     for (int kb = 0; kb < 2; ++kb) Sx[kb] = ks == 0 ? MFMA(kf[kb][0], qf[0], minit) : MFMA(kf[kb][ks], qf[ks], Sx[kb]);
;             }
;             if (kt * 64 + 63 > q0) {
; #pragma unroll
;                 for (int kb = 0; kb < 2; ++kb)
; #pragma unroll
;                     for (int i = 0; i < 16; ++i) {
;                         float p = fexp2(Sx[kb][i]);
;                         const int key = kt * 64 + 32 * kb + (i & 3) + 8 * (i >> 2) + 4 * h;
;                         if (key > qpos) p = 0.f;
;                         lsum += p; Sx[kb][i] = p;
;                     }
;             } else {
;                 float l0 = 0.f, l1 = 0.f;
; #pragma unroll
;                 for (int i = 0; i < 16; ++i) { const float p0 = fexp2(Sx[0][i]), p1 = fexp2(Sx[1][i]); l0 += p0; l1 += p1; Sx[0][i] = p0; Sx[1][i] = p1; }
;                 lsum += l0 + l1;
;             }
;             bf16x8 pf[4];
;             pf[0] = pack8(Sx[0], 0); pf[1] = pack8(Sx[0], 1); pf[2] = pack8(Sx[1], 0); pf[3] = pack8(Sx[1], 1);
;             {
;                 bf16x8 vf[2][4];
; #pragma unroll
.Ldf_fast:
	s_and_b32 s30, 1, s54
	s_cselect_b32 s28, 0x6000, 0
	s_cselect_b32 s30, 0, 0x6000
	v_or_b32_e32 v0, s30, v188
	v_add_u32_e32 v195, v0, v189
	v_add_u32_e32 v194, v0, v190
	v_add_u32_e32 v193, v0, v191
	v_add_u32_e32 v0, v0, v192
	ds_read_b128 v[2:5], v195
	ds_read_b128 v[10:13], v194
	ds_read_b128 v[200:203], v193
	ds_read_b128 v[208:211], v0
	ds_read_b128 v[6:9], v195 offset:4096
	ds_read_b128 v[196:199], v194 offset:4096
	ds_read_b128 v[204:207], v193 offset:4096
	ds_read_b128 v[212:215], v0 offset:4096
	v_add_u32_e32 v112, s28, v187
	v_lshl_add_u64 v[114:115], v[160:161], 0, v[158:159]
	v_lshl_add_u64 v[120:121], v[164:165], 0, v[158:159]
	v_readfirstlane_b32 s28, v112
	s_mov_b32 m0, s28
	v_add_u32_e32 v118, 0x2000, v112
	global_load_lds_dwordx4 v[114:115], off
	s_mov_b64 s[28:29], 0x1b800080
	v_lshl_add_u64 v[116:117], v[120:121], 0, s[28:29]
	v_readfirstlane_b32 s28, v118
	s_mov_b32 m0, s28
	s_mov_b64 s[28:29], 0x1b900080
	v_add_u32_e32 v112, 0x4000, v112
	v_lshl_add_u64 v[120:121], v[120:121], 0, s[28:29]
	v_mov_b32_e32 v14, 0
	v_mov_b32_e32 v15, 0
	s_waitcnt lgkmcnt(7)
	v_mfma_f32_32x32x16_bf16 v[96:111], v[2:5], v[140:143], v[16:31]
	global_load_lds_dwordx4 v[116:117], off
	v_readfirstlane_b32 s28, v112
	s_mov_b32 m0, s28
	s_waitcnt lgkmcnt(6)
	v_mfma_f32_32x32x16_bf16 v[96:111], v[10:13], v[136:139], v[96:111]
	global_load_lds_dwordx4 v[120:121], off
	s_waitcnt lgkmcnt(5)
	v_mfma_f32_32x32x16_bf16 v[96:111], v[200:203], v[132:135], v[96:111]
	s_waitcnt lgkmcnt(4)
	v_mfma_f32_32x32x16_bf16 v[96:111], v[208:211], v[128:131], v[96:111]
	s_waitcnt lgkmcnt(3)
	v_mfma_f32_32x32x16_bf16 v[112:127], v[6:9], v[140:143], v[16:31]
	ds_read_b128 v[2:5], v195 offset:8192
	ds_read_b128 v[10:13], v195 offset:12288
	s_waitcnt lgkmcnt(4)
	v_mfma_f32_32x32x16_bf16 v[112:127], v[196:199], v[136:139], v[112:127]
	ds_read_b128 v[200:203], v195 offset:16384
	ds_read_b128 v[208:211], v195 offset:20480
	s_nop 3
	v_exp_f32_e32 v96, v96
	v_exp_f32_e32 v97, v97
	v_add_f32_e32 v14, v14, v96
	v_add_f32_e32 v14, v14, v97
	s_waitcnt lgkmcnt(5)
	v_mfma_f32_32x32x16_bf16 v[112:127], v[204:207], v[132:135], v[112:127]
	v_exp_f32_e32 v98, v98
	v_exp_f32_e32 v99, v99
	v_add_f32_e32 v14, v14, v98
	v_add_f32_e32 v14, v14, v99
	s_waitcnt lgkmcnt(4)
	v_mfma_f32_32x32x16_bf16 v[112:127], v[212:215], v[128:131], v[112:127]
	v_exp_f32_e32 v100, v100
	v_exp_f32_e32 v101, v101
	v_add_f32_e32 v14, v14, v100
	v_add_f32_e32 v14, v14, v101
	v_exp_f32_e32 v102, v102
	v_exp_f32_e32 v103, v103
	v_add_f32_e32 v14, v14, v102
	v_add_f32_e32 v14, v14, v103
	v_cvt_pk_bf16_f32 v96, v96, v97
	v_cvt_pk_bf16_f32 v97, v98, v99
	v_cvt_pk_bf16_f32 v98, v100, v101
	v_cvt_pk_bf16_f32 v99, v102, v103
	s_waitcnt lgkmcnt(3)
	s_nop 0
	v_mfma_f32_32x32x16_bf16 v[80:95], v[2:5], v[96:99], v[80:95]
	ds_read_b128 v[6:9], v194 offset:8192
	ds_read_b128 v[196:199], v194 offset:12288
	ds_read_b128 v[204:207], v194 offset:16384
	ds_read_b128 v[212:215], v194 offset:20480
	v_exp_f32_e32 v104, v104
	v_exp_f32_e32 v105, v105
	v_add_f32_e32 v14, v14, v104
	v_add_f32_e32 v14, v14, v105
	s_waitcnt lgkmcnt(6)
	v_mfma_f32_32x32x16_bf16 v[64:79], v[10:13], v[96:99], v[64:79]
	ds_read_b128 v[2:5], v193 offset:8192
	v_exp_f32_e32 v106, v106
	v_exp_f32_e32 v107, v107
	v_add_f32_e32 v14, v14, v106
	v_add_f32_e32 v14, v14, v107
	s_waitcnt lgkmcnt(6)
	v_mfma_f32_32x32x16_bf16 v[48:63], v[200:203], v[96:99], v[48:63]
	ds_read_b128 v[10:13], v193 offset:12288
	v_exp_f32_e32 v108, v108
	v_exp_f32_e32 v109, v109
	v_add_f32_e32 v14, v14, v108
	v_add_f32_e32 v14, v14, v109
	s_waitcnt lgkmcnt(6)
	v_mfma_f32_32x32x16_bf16 v[32:47], v[208:211], v[96:99], v[32:47]
	ds_read_b128 v[200:203], v193 offset:16384
	v_exp_f32_e32 v110, v110
	v_exp_f32_e32 v111, v111
	v_add_f32_e32 v14, v14, v110
	v_add_f32_e32 v14, v14, v111
	v_cvt_pk_bf16_f32 v104, v104, v105
	v_cvt_pk_bf16_f32 v105, v106, v107
	v_cvt_pk_bf16_f32 v106, v108, v109
	v_cvt_pk_bf16_f32 v107, v110, v111
	s_waitcnt lgkmcnt(6)
	s_nop 0
	v_mfma_f32_32x32x16_bf16 v[80:95], v[6:9], v[104:107], v[80:95]
	ds_read_b128 v[208:211], v193 offset:20480
	v_exp_f32_e32 v112, v112
	v_exp_f32_e32 v113, v113
	v_add_f32_e32 v15, v15, v112
	v_add_f32_e32 v15, v15, v113
	s_waitcnt lgkmcnt(6)
	v_mfma_f32_32x32x16_bf16 v[64:79], v[196:199], v[104:107], v[64:79]
	ds_read_b128 v[6:9], v0 offset:8192
	v_exp_f32_e32 v114, v114
	v_exp_f32_e32 v115, v115
	v_add_f32_e32 v15, v15, v114
	v_add_f32_e32 v15, v15, v115
	s_waitcnt lgkmcnt(6)
	v_mfma_f32_32x32x16_bf16 v[48:63], v[204:207], v[104:107], v[48:63]
	ds_read_b128 v[196:199], v0 offset:12288
	v_exp_f32_e32 v116, v116
	v_exp_f32_e32 v117, v117
	v_add_f32_e32 v15, v15, v116
	v_add_f32_e32 v15, v15, v117
	s_waitcnt lgkmcnt(6)
	v_mfma_f32_32x32x16_bf16 v[32:47], v[212:215], v[104:107], v[32:47]
	ds_read_b128 v[204:207], v0 offset:16384
	v_exp_f32_e32 v118, v118
	v_exp_f32_e32 v119, v119
	v_add_f32_e32 v15, v15, v118
	v_add_f32_e32 v15, v15, v119
	v_cvt_pk_bf16_f32 v112, v112, v113
	v_cvt_pk_bf16_f32 v113, v114, v115
	v_cvt_pk_bf16_f32 v114, v116, v117
	v_cvt_pk_bf16_f32 v115, v118, v119
	s_waitcnt lgkmcnt(6)
	s_nop 0
	v_mfma_f32_32x32x16_bf16 v[80:95], v[2:5], v[112:115], v[80:95]
	ds_read_b128 v[212:215], v0 offset:20480
	v_exp_f32_e32 v120, v120
	v_exp_f32_e32 v121, v121
	v_add_f32_e32 v15, v15, v120
	v_add_f32_e32 v15, v15, v121
	s_waitcnt lgkmcnt(6)
	v_mfma_f32_32x32x16_bf16 v[64:79], v[10:13], v[112:115], v[64:79]
	v_exp_f32_e32 v122, v122
	v_exp_f32_e32 v123, v123
	v_add_f32_e32 v15, v15, v122
	v_add_f32_e32 v15, v15, v123
	s_waitcnt lgkmcnt(5)
	v_mfma_f32_32x32x16_bf16 v[48:63], v[200:203], v[112:115], v[48:63]
	v_exp_f32_e32 v124, v124
	v_exp_f32_e32 v125, v125
	v_add_f32_e32 v15, v15, v124
	v_add_f32_e32 v15, v15, v125
	s_waitcnt lgkmcnt(4)
	v_mfma_f32_32x32x16_bf16 v[32:47], v[208:211], v[112:115], v[32:47]
	v_exp_f32_e32 v126, v126
	v_exp_f32_e32 v127, v127
	v_add_f32_e32 v15, v15, v126
	v_add_f32_e32 v15, v15, v127
	v_cvt_pk_bf16_f32 v120, v120, v121
	v_cvt_pk_bf16_f32 v121, v122, v123
	v_cvt_pk_bf16_f32 v122, v124, v125
	v_cvt_pk_bf16_f32 v123, v126, v127
	v_add_f32_e32 v14, v14, v15
	s_waitcnt lgkmcnt(3)
	v_mfma_f32_32x32x16_bf16 v[80:95], v[6:9], v[120:123], v[80:95]
	v_add_f32_e32 v186, v186, v14
	s_waitcnt lgkmcnt(2)
	v_mfma_f32_32x32x16_bf16 v[64:79], v[196:199], v[120:123], v[64:79]
	s_waitcnt lgkmcnt(1)
	v_mfma_f32_32x32x16_bf16 v[48:63], v[204:207], v[120:123], v[48:63]
	s_waitcnt lgkmcnt(0)
	v_mfma_f32_32x32x16_bf16 v[32:47], v[212:215], v[120:123], v[32:47]
	s_branch .Ldf_join
